# fused final-norm epilogue: residual loads of rows 1..7 issued behind row 0 (one counted wait per row instead of 8 serial round trips)
# speedup vs baseline: 1.0296x; 1.0022x over previous
; __device__ __forceinline__ float bflo(unsigned u) { return __uint_as_float(u << 16); }
; __device__ __forceinline__ float bfhi(unsigned u) { return __uint_as_float(u & 0xffff0000u); }
; __device__ __forceinline__ float dot4(f32x4 v) { return (v[0] * v[0] + v[1] * v[1]) + (v[2] * v[2] + v[3] * v[3]); }
; __device__ __forceinline__ float quad_sum(float s) { s += __shfl_xor(s, 16); s += __shfl_xor(s, 32); return s; }
; __device__ __forceinline__ void epi_final(f32x4 (&acc)[2][2][4][2], const Unit& u, int wr, int wc, int fr, int fq, const EpiArgs& E, LAS float* rt) {
;     ...
;             const int row = rowb + ai * HALF + m * 16; float ss = 0.f;
; #pragma unroll
;             for (int bj = 0; bj < 2; ++bj) { const int col = u.pn * BM + bj * HALF + wc * 32 + fq * 8;
;                 const u32x4 rb = *(const u32x4*)(E.res + (size_t)row * 1024 + col);
;                 acc[ai][bj][m][0] += (f32x4){bflo(rb.x), bfhi(rb.x), bflo(rb.y), bfhi(rb.y)};
;                 acc[ai][bj][m][1] += (f32x4){bflo(rb.z), bfhi(rb.z), bflo(rb.w), bfhi(rb.w)};
;                 ss += dot4(acc[ai][bj][m][0]) + dot4(acc[ai][bj][m][1]); }
;             ss = quad_sum(ss);
;             if (fq == 0) __hip_atomic_store((unsigned*)E.stOut + (size_t)row * 16 + u.pn * 4 + wc, __float_as_uint(ss), __ATOMIC_RELAXED, __HIP_MEMORY_SCOPE_AGENT);
.LBB0_1408:
	s_lshl_b32 s8, s46, 8
	s_add_i32 s1, s8, s47
	s_lshl_b32 s0, s50, 5
	v_or_b32_e32 v130, s1, v1
	s_lshl_b32 s1, s51, 8
	s_or_b32 s0, s1, s0
	v_ashrrev_i32_e32 v131, 31, v130
	v_lshl_or_b32 v132, v153, 3, s0
	v_lshlrev_b64 v[134:135], 11, v[130:131]
	v_lshl_add_u64 v[134:135], s[62:63], 0, v[134:135]
	v_ashrrev_i32_e32 v133, 31, v132
	v_lshl_add_u64 v[138:139], v[132:133], 1, v[134:135]
	s_waitcnt vmcnt(0)
	s_barrier
	v_mov_b64_e32 v[230:231], v[138:139]
	global_load_dwordx4 v[134:137], v[138:139], off
	s_nop 0
	global_load_dwordx4 v[138:141], v[138:139], off offset:256
	s_mov_b64 s[98:99], 0x8000
	v_lshl_add_u64 v[228:229], v[230:231], 0, s[98:99]
	global_load_dwordx4 v[172:175], v[228:229], off
	global_load_dwordx4 v[176:179], v[228:229], off offset:256
	s_mov_b64 s[98:99], 0x10000
	v_lshl_add_u64 v[228:229], v[230:231], 0, s[98:99]
	global_load_dwordx4 v[180:183], v[228:229], off
	global_load_dwordx4 v[184:187], v[228:229], off offset:256
	s_mov_b64 s[98:99], 0x18000
	v_lshl_add_u64 v[228:229], v[230:231], 0, s[98:99]
	global_load_dwordx4 v[188:191], v[228:229], off
	global_load_dwordx4 v[192:195], v[228:229], off offset:256
	s_mov_b64 s[98:99], 0x40000
	v_lshl_add_u64 v[228:229], v[230:231], 0, s[98:99]
	global_load_dwordx4 v[196:199], v[228:229], off
	global_load_dwordx4 v[200:203], v[228:229], off offset:256
	s_mov_b64 s[98:99], 0x48000
	v_lshl_add_u64 v[228:229], v[230:231], 0, s[98:99]
	global_load_dwordx4 v[204:207], v[228:229], off
	global_load_dwordx4 v[208:211], v[228:229], off offset:256
	s_mov_b64 s[98:99], 0x50000
	v_lshl_add_u64 v[228:229], v[230:231], 0, s[98:99]
	global_load_dwordx4 v[212:215], v[228:229], off
	global_load_dwordx4 v[216:219], v[228:229], off offset:256
	s_mov_b64 s[98:99], 0x58000
	v_lshl_add_u64 v[228:229], v[230:231], 0, s[98:99]
	global_load_dwordx4 v[220:223], v[228:229], off
	global_load_dwordx4 v[224:227], v[228:229], off offset:256
	v_mbcnt_hi_u32_b32 v148, -1, v152
	v_and_b32_e32 v143, 64, v148
	v_xor_b32_e32 v142, 16, v148
	v_add_u32_e32 v149, 64, v143
	v_cmp_lt_i32_e32 vcc, v142, v149
	s_lshl_b32 s0, s51, 2
	v_readfirstlane_b32 s9, v0
	v_cndmask_b32_e32 v142, v148, v142, vcc
	v_lshlrev_b32_e32 v152, 2, v142
	s_mov_b32 s5, 0
	s_ashr_i32 s1, s0, 31
	s_waitcnt vmcnt(14)
	v_lshlrev_b32_e32 v142, 16, v134
	v_and_b32_e32 v143, 0xffff0000, v134
	v_lshlrev_b32_e32 v134, 16, v135
	v_and_b32_e32 v135, 0xffff0000, v135
	v_lshlrev_b32_e32 v144, 16, v136
	v_and_b32_e32 v145, 0xffff0000, v136
	v_lshlrev_b32_e32 v136, 16, v137
	v_and_b32_e32 v137, 0xffff0000, v137
	v_lshlrev_b32_e32 v146, 16, v138
	v_and_b32_e32 v147, 0xffff0000, v138
	v_lshlrev_b32_e32 v138, 16, v139
	v_and_b32_e32 v139, 0xffff0000, v139
	v_lshlrev_b32_e32 v154, 16, v140
	v_and_b32_e32 v155, 0xffff0000, v140
	v_lshlrev_b32_e32 v140, 16, v141
	v_and_b32_e32 v141, 0xffff0000, v141
	v_pk_add_f32 v[128:129], v[128:129], v[134:135]
	v_pk_add_f32 v[126:127], v[126:127], v[142:143]
	v_pk_add_f32 v[124:125], v[124:125], v[136:137]
	v_pk_add_f32 v[122:123], v[122:123], v[144:145]
	v_pk_add_f32 v[120:121], v[120:121], v[138:139]
	v_pk_add_f32 v[118:119], v[118:119], v[146:147]
	v_pk_add_f32 v[116:117], v[116:117], v[140:141]
	v_pk_add_f32 v[114:115], v[114:115], v[154:155]
	v_mul_f32_e32 v134, v127, v127
	v_mul_f32_e32 v135, v129, v129
	v_mul_f32_e32 v136, v123, v123
	v_mul_f32_e32 v137, v125, v125
	v_mul_f32_e32 v138, v119, v119
	v_mul_f32_e32 v139, v121, v121
	v_mul_f32_e32 v140, v115, v115
	v_mul_f32_e32 v141, v117, v117
	v_fmac_f32_e32 v134, v126, v126
	v_fmac_f32_e32 v135, v128, v128
	v_fmac_f32_e32 v136, v122, v122
	v_fmac_f32_e32 v137, v124, v124
	v_fmac_f32_e32 v138, v118, v118
	v_fmac_f32_e32 v139, v120, v120
	v_fmac_f32_e32 v140, v114, v114
	v_fmac_f32_e32 v141, v116, v116
	v_add_f32_e32 v134, v134, v135
	v_add_f32_e32 v135, v136, v137
	v_add_f32_e32 v136, v138, v139
	v_add_f32_e32 v137, v140, v141
	v_add_f32_e32 v134, v134, v135
	v_add_f32_e32 v135, v136, v137
	v_add_f32_e32 v134, v134, v135
	ds_bpermute_b32 v135, v152, v134
	v_xor_b32_e32 v136, 32, v148
	v_cmp_lt_i32_e32 vcc, v136, v149
	s_waitcnt lgkmcnt(0)
	v_add_f32_e32 v134, v134, v135
	v_cndmask_b32_e32 v136, v148, v136, vcc
	v_lshlrev_b32_e32 v154, 2, v136
	ds_bpermute_b32 v135, v154, v134
	v_cmp_eq_u32_e32 vcc, 0, v153
	s_and_saveexec_b64 s[6:7], vcc
	s_cbranch_execz .LBB0_1410
	s_waitcnt lgkmcnt(0)
	v_add_f32_e32 v136, v134, v135
	v_lshlrev_b64 v[134:135], 6, v[130:131]
	v_lshl_add_u64 v[134:135], s[10:11], 0, v[134:135]
	v_lshl_add_u64 v[134:135], s[0:1], 2, v[134:135]
	s_lshl_b32 s4, s50, 2
	v_lshl_add_u64 v[134:135], v[134:135], 0, s[4:5]
	global_store_dword v[134:135], v136, off sc1
; __device__ __forceinline__ float bflo(unsigned u) { return __uint_as_float(u << 16); }
; __device__ __forceinline__ float bfhi(unsigned u) { return __uint_as_float(u & 0xffff0000u); }
; __device__ __forceinline__ float dot4(f32x4 v) { return (v[0] * v[0] + v[1] * v[1]) + (v[2] * v[2] + v[3] * v[3]); }
; __device__ __forceinline__ float quad_sum(float s) { s += __shfl_xor(s, 16); s += __shfl_xor(s, 32); return s; }
; __device__ __forceinline__ void epi_final(f32x4 (&acc)[2][2][4][2], const Unit& u, int wr, int wc, int fr, int fq, const EpiArgs& E, LAS float* rt) {
;     ...
;             const int row = rowb + ai * HALF + m * 16; float ss = 0.f;
; #pragma unroll
;             for (int bj = 0; bj < 2; ++bj) { const int col = u.pn * BM + bj * HALF + wc * 32 + fq * 8;
;                 const u32x4 rb = *(const u32x4*)(E.res + (size_t)row * 1024 + col);
;                 acc[ai][bj][m][0] += (f32x4){bflo(rb.x), bfhi(rb.x), bflo(rb.y), bfhi(rb.y)};
;                 acc[ai][bj][m][1] += (f32x4){bflo(rb.z), bfhi(rb.z), bflo(rb.w), bfhi(rb.w)};
;                 ss += dot4(acc[ai][bj][m][0]) + dot4(acc[ai][bj][m][1]); }
;             ss = quad_sum(ss);
;             if (fq == 0) __hip_atomic_store((unsigned*)E.stOut + (size_t)row * 16 + u.pn * 4 + wc, __float_as_uint(ss), __ATOMIC_RELAXED, __HIP_MEMORY_SCOPE_AGENT);
.LBB0_1410:
	s_or_b64 exec, exec, s[6:7]
	v_or_b32_e32 v134, 16, v130
	s_waitcnt lgkmcnt(0)
	v_ashrrev_i32_e32 v135, 31, v134
	v_lshlrev_b64 v[136:137], 11, v[134:135]
	v_lshl_add_u64 v[136:137], s[62:63], 0, v[136:137]
	v_lshl_add_u64 v[140:141], v[132:133], 1, v[136:137]
	s_waitcnt vmcnt(13)
	v_mov_b32_e32 v136, v172
	v_mov_b32_e32 v137, v173
	v_mov_b32_e32 v138, v174
	v_mov_b32_e32 v139, v175
	v_lshlrev_b32_e32 v144, 16, v136
	v_and_b32_e32 v145, 0xffff0000, v136
	v_lshlrev_b32_e32 v136, 16, v137
	v_and_b32_e32 v137, 0xffff0000, v137
	v_lshlrev_b32_e32 v146, 16, v138
	v_and_b32_e32 v147, 0xffff0000, v138
	v_lshlrev_b32_e32 v138, 16, v139
	v_and_b32_e32 v139, 0xffff0000, v139
	v_mov_b32_e32 v140, v176
	v_mov_b32_e32 v141, v177
	v_mov_b32_e32 v142, v178
	v_mov_b32_e32 v143, v179
	v_lshlrev_b32_e32 v156, 16, v140
	v_and_b32_e32 v157, 0xffff0000, v140
	v_lshlrev_b32_e32 v140, 16, v141
	v_and_b32_e32 v141, 0xffff0000, v141
	v_lshlrev_b32_e32 v158, 16, v142
	v_and_b32_e32 v159, 0xffff0000, v142
	v_lshlrev_b32_e32 v142, 16, v143
	v_and_b32_e32 v143, 0xffff0000, v143
	v_pk_add_f32 v[112:113], v[112:113], v[136:137]
	v_pk_add_f32 v[136:137], v[110:111], v[144:145]
	v_pk_add_f32 v[108:109], v[108:109], v[138:139]
	v_pk_add_f32 v[106:107], v[106:107], v[146:147]
	v_pk_add_f32 v[104:105], v[104:105], v[140:141]
	v_pk_add_f32 v[102:103], v[102:103], v[156:157]
	v_pk_add_f32 v[100:101], v[100:101], v[142:143]
	v_pk_add_f32 v[98:99], v[98:99], v[158:159]
	v_mul_f32_e32 v110, v137, v137
	v_mul_f32_e32 v111, v113, v113
	v_mul_f32_e32 v138, v107, v107
	v_mul_f32_e32 v139, v109, v109
	v_mul_f32_e32 v140, v103, v103
	v_mul_f32_e32 v141, v105, v105
	v_mul_f32_e32 v142, v99, v99
	v_mul_f32_e32 v143, v101, v101
	v_fmac_f32_e32 v110, v136, v136
	v_fmac_f32_e32 v111, v112, v112
	v_fmac_f32_e32 v138, v106, v106
	v_fmac_f32_e32 v139, v108, v108
	v_fmac_f32_e32 v140, v102, v102
	v_fmac_f32_e32 v141, v104, v104
	v_fmac_f32_e32 v142, v98, v98
	v_fmac_f32_e32 v143, v100, v100
	v_add_f32_e32 v110, v110, v111
	v_add_f32_e32 v111, v138, v139
	v_add_f32_e32 v138, v140, v141
	v_add_f32_e32 v139, v142, v143
	v_add_f32_e32 v110, v110, v111
	v_add_f32_e32 v111, v138, v139
	v_add_f32_e32 v110, v110, v111
	ds_bpermute_b32 v111, v152, v110
	s_waitcnt lgkmcnt(0)
	v_add_f32_e32 v110, v110, v111
	ds_bpermute_b32 v111, v154, v110
	s_and_saveexec_b64 s[4:5], vcc
	s_cbranch_execz .LBB0_1412
	s_waitcnt lgkmcnt(0)
	v_add_f32_e32 v138, v110, v111
	v_lshlrev_b64 v[110:111], 6, v[134:135]
	v_lshl_add_u64 v[110:111], s[10:11], 0, v[110:111]
	v_lshl_add_u64 v[110:111], s[0:1], 2, v[110:111]
	s_lshl_b32 s6, s50, 2
	s_mov_b32 s7, 0
	v_lshl_add_u64 v[110:111], v[110:111], 0, s[6:7]
	global_store_dword v[110:111], v138, off sc1
.LBB0_1412:
	s_or_b64 exec, exec, s[4:5]
	v_or_b32_e32 v110, 32, v130
	s_waitcnt lgkmcnt(0)
	v_ashrrev_i32_e32 v111, 31, v110
	v_lshlrev_b64 v[138:139], 11, v[110:111]
	v_lshl_add_u64 v[138:139], s[62:63], 0, v[138:139]
	v_lshl_add_u64 v[142:143], v[132:133], 1, v[138:139]
	s_waitcnt vmcnt(12)
	v_mov_b32_e32 v138, v180
	v_mov_b32_e32 v139, v181
	v_mov_b32_e32 v140, v182
	v_mov_b32_e32 v141, v183
	v_lshlrev_b32_e32 v146, 16, v138
	v_and_b32_e32 v147, 0xffff0000, v138
	v_lshlrev_b32_e32 v138, 16, v139
	v_and_b32_e32 v139, 0xffff0000, v139
	v_lshlrev_b32_e32 v156, 16, v140
	v_and_b32_e32 v157, 0xffff0000, v140
	v_lshlrev_b32_e32 v140, 16, v141
	v_and_b32_e32 v141, 0xffff0000, v141
	v_mov_b32_e32 v142, v184
	v_mov_b32_e32 v143, v185
	v_mov_b32_e32 v144, v186
	v_mov_b32_e32 v145, v187
	v_lshlrev_b32_e32 v158, 16, v142
	v_and_b32_e32 v159, 0xffff0000, v142
	v_lshlrev_b32_e32 v142, 16, v143
	v_and_b32_e32 v143, 0xffff0000, v143
	v_lshlrev_b32_e32 v160, 16, v144
	v_and_b32_e32 v161, 0xffff0000, v144
	v_lshlrev_b32_e32 v144, 16, v145
	v_and_b32_e32 v145, 0xffff0000, v145
	v_pk_add_f32 v[96:97], v[96:97], v[138:139]
	v_pk_add_f32 v[94:95], v[94:95], v[146:147]
	v_pk_add_f32 v[92:93], v[92:93], v[140:141]
	v_pk_add_f32 v[90:91], v[90:91], v[156:157]
	v_pk_add_f32 v[88:89], v[88:89], v[142:143]
	v_pk_add_f32 v[86:87], v[86:87], v[158:159]
	v_pk_add_f32 v[84:85], v[84:85], v[144:145]
	v_pk_add_f32 v[82:83], v[82:83], v[160:161]
	v_mul_f32_e32 v138, v95, v95
	v_mul_f32_e32 v139, v97, v97
	v_mul_f32_e32 v140, v91, v91
	v_mul_f32_e32 v141, v93, v93
	v_mul_f32_e32 v142, v87, v87
	v_mul_f32_e32 v143, v89, v89
	v_mul_f32_e32 v144, v83, v83
	v_mul_f32_e32 v145, v85, v85
	v_fmac_f32_e32 v138, v94, v94
	v_fmac_f32_e32 v139, v96, v96
	v_fmac_f32_e32 v140, v90, v90
	v_fmac_f32_e32 v141, v92, v92
	v_fmac_f32_e32 v142, v86, v86
	v_fmac_f32_e32 v143, v88, v88
	v_fmac_f32_e32 v144, v82, v82
	v_fmac_f32_e32 v145, v84, v84
	v_add_f32_e32 v138, v138, v139
	v_add_f32_e32 v139, v140, v141
	v_add_f32_e32 v140, v142, v143
	v_add_f32_e32 v141, v144, v145
	v_add_f32_e32 v138, v138, v139
	v_add_f32_e32 v139, v140, v141
	v_add_f32_e32 v138, v138, v139
	ds_bpermute_b32 v139, v152, v138
	s_waitcnt lgkmcnt(0)
	v_add_f32_e32 v138, v138, v139
	ds_bpermute_b32 v139, v154, v138
	s_and_saveexec_b64 s[4:5], vcc
	s_cbranch_execz .LBB0_1414
	s_waitcnt lgkmcnt(0)
	v_add_f32_e32 v140, v138, v139
	v_lshlrev_b64 v[138:139], 6, v[110:111]
	v_lshl_add_u64 v[138:139], s[10:11], 0, v[138:139]
	v_lshl_add_u64 v[138:139], s[0:1], 2, v[138:139]
	s_lshl_b32 s6, s50, 2
	s_mov_b32 s7, 0
	v_lshl_add_u64 v[138:139], v[138:139], 0, s[6:7]
	global_store_dword v[138:139], v140, off sc1
; __device__ __forceinline__ float bflo(unsigned u) { return __uint_as_float(u << 16); }
; __device__ __forceinline__ float bfhi(unsigned u) { return __uint_as_float(u & 0xffff0000u); }
; __device__ __forceinline__ float dot4(f32x4 v) { return (v[0] * v[0] + v[1] * v[1]) + (v[2] * v[2] + v[3] * v[3]); }
; __device__ __forceinline__ float quad_sum(float s) { s += __shfl_xor(s, 16); s += __shfl_xor(s, 32); return s; }
; __device__ __forceinline__ void epi_final(f32x4 (&acc)[2][2][4][2], const Unit& u, int wr, int wc, int fr, int fq, const EpiArgs& E, LAS float* rt) {
;     ...
;             const int row = rowb + ai * HALF + m * 16; float ss = 0.f;
; #pragma unroll
;             for (int bj = 0; bj < 2; ++bj) { const int col = u.pn * BM + bj * HALF + wc * 32 + fq * 8;
;                 const u32x4 rb = *(const u32x4*)(E.res + (size_t)row * 1024 + col);
;                 acc[ai][bj][m][0] += (f32x4){bflo(rb.x), bfhi(rb.x), bflo(rb.y), bfhi(rb.y)};
;                 acc[ai][bj][m][1] += (f32x4){bflo(rb.z), bfhi(rb.z), bflo(rb.w), bfhi(rb.w)};
;                 ss += dot4(acc[ai][bj][m][0]) + dot4(acc[ai][bj][m][1]); }
;             ss = quad_sum(ss);
;             if (fq == 0) __hip_atomic_store((unsigned*)E.stOut + (size_t)row * 16 + u.pn * 4 + wc, __float_as_uint(ss), __ATOMIC_RELAXED, __HIP_MEMORY_SCOPE_AGENT);
.LBB0_1414:
	s_or_b64 exec, exec, s[4:5]
	v_or_b32_e32 v138, 48, v130
	s_waitcnt lgkmcnt(0)
	v_ashrrev_i32_e32 v139, 31, v138
	v_lshlrev_b64 v[140:141], 11, v[138:139]
	v_lshl_add_u64 v[140:141], s[62:63], 0, v[140:141]
	v_lshl_add_u64 v[144:145], v[132:133], 1, v[140:141]
	s_waitcnt vmcnt(11)
	v_mov_b32_e32 v140, v188
	v_mov_b32_e32 v141, v189
	v_mov_b32_e32 v142, v190
	v_mov_b32_e32 v143, v191
	v_lshlrev_b32_e32 v156, 16, v140
	v_and_b32_e32 v157, 0xffff0000, v140
	v_lshlrev_b32_e32 v140, 16, v141
	v_and_b32_e32 v141, 0xffff0000, v141
	v_lshlrev_b32_e32 v158, 16, v142
	v_and_b32_e32 v159, 0xffff0000, v142
	v_lshlrev_b32_e32 v142, 16, v143
	v_and_b32_e32 v143, 0xffff0000, v143
	v_mov_b32_e32 v144, v192
	v_mov_b32_e32 v145, v193
	v_mov_b32_e32 v146, v194
	v_mov_b32_e32 v147, v195
	v_lshlrev_b32_e32 v160, 16, v144
	v_and_b32_e32 v161, 0xffff0000, v144
	v_lshlrev_b32_e32 v144, 16, v145
	v_and_b32_e32 v145, 0xffff0000, v145
	v_lshlrev_b32_e32 v162, 16, v146
	v_and_b32_e32 v163, 0xffff0000, v146
	v_lshlrev_b32_e32 v146, 16, v147
	v_and_b32_e32 v147, 0xffff0000, v147
	v_pk_add_f32 v[80:81], v[80:81], v[140:141]
	v_pk_add_f32 v[140:141], v[78:79], v[156:157]
	v_pk_add_f32 v[76:77], v[76:77], v[142:143]
	v_pk_add_f32 v[74:75], v[74:75], v[158:159]
	v_pk_add_f32 v[72:73], v[72:73], v[144:145]
	v_pk_add_f32 v[70:71], v[70:71], v[160:161]
	v_pk_add_f32 v[68:69], v[68:69], v[146:147]
	v_pk_add_f32 v[66:67], v[66:67], v[162:163]
	v_mul_f32_e32 v78, v141, v141
	v_mul_f32_e32 v79, v81, v81
	v_mul_f32_e32 v142, v75, v75
	v_mul_f32_e32 v143, v77, v77
	v_mul_f32_e32 v144, v71, v71
	v_mul_f32_e32 v145, v73, v73
	v_mul_f32_e32 v146, v67, v67
	v_mul_f32_e32 v147, v69, v69
	v_fmac_f32_e32 v78, v140, v140
	v_fmac_f32_e32 v79, v80, v80
	v_fmac_f32_e32 v142, v74, v74
	v_fmac_f32_e32 v143, v76, v76
	v_fmac_f32_e32 v144, v70, v70
	v_fmac_f32_e32 v145, v72, v72
	v_fmac_f32_e32 v146, v66, v66
	v_fmac_f32_e32 v147, v68, v68
	v_add_f32_e32 v78, v78, v79
	v_add_f32_e32 v79, v142, v143
	v_add_f32_e32 v142, v144, v145
	v_add_f32_e32 v143, v146, v147
	v_add_f32_e32 v78, v78, v79
	v_add_f32_e32 v79, v142, v143
	v_add_f32_e32 v78, v78, v79
	ds_bpermute_b32 v79, v152, v78
	s_waitcnt lgkmcnt(0)
	v_add_f32_e32 v78, v78, v79
	ds_bpermute_b32 v79, v154, v78
	s_and_saveexec_b64 s[4:5], vcc
	s_cbranch_execz .LBB0_1416
	s_waitcnt lgkmcnt(0)
	v_add_f32_e32 v142, v78, v79
	v_lshlrev_b64 v[78:79], 6, v[138:139]
	v_lshl_add_u64 v[78:79], s[10:11], 0, v[78:79]
	v_lshl_add_u64 v[78:79], s[0:1], 2, v[78:79]
	s_lshl_b32 s6, s50, 2
	s_mov_b32 s7, 0
	v_lshl_add_u64 v[78:79], v[78:79], 0, s[6:7]
	global_store_dword v[78:79], v142, off sc1
.LBB0_1416:
	s_or_b64 exec, exec, s[4:5]
	v_add_u32_e32 v78, 0x80, v130
	s_waitcnt lgkmcnt(0)
	v_ashrrev_i32_e32 v79, 31, v78
	v_lshlrev_b64 v[142:143], 11, v[78:79]
	v_lshl_add_u64 v[142:143], s[62:63], 0, v[142:143]
	v_lshl_add_u64 v[146:147], v[132:133], 1, v[142:143]
	s_waitcnt vmcnt(10)
	v_mov_b32_e32 v142, v196
	v_mov_b32_e32 v143, v197
	v_mov_b32_e32 v144, v198
	v_mov_b32_e32 v145, v199
	v_lshlrev_b32_e32 v146, 16, v142
	v_and_b32_e32 v147, 0xffff0000, v142
	v_lshlrev_b32_e32 v142, 16, v143
	v_and_b32_e32 v143, 0xffff0000, v143
	v_lshlrev_b32_e32 v160, 16, v144
	v_and_b32_e32 v161, 0xffff0000, v144
	v_lshlrev_b32_e32 v144, 16, v145
	v_and_b32_e32 v145, 0xffff0000, v145
	v_mov_b32_e32 v156, v200
	v_mov_b32_e32 v157, v201
	v_mov_b32_e32 v158, v202
	v_mov_b32_e32 v159, v203
	v_lshlrev_b32_e32 v162, 16, v156
	v_and_b32_e32 v163, 0xffff0000, v156
	v_lshlrev_b32_e32 v156, 16, v157
	v_and_b32_e32 v157, 0xffff0000, v157
	v_lshlrev_b32_e32 v164, 16, v158
	v_and_b32_e32 v165, 0xffff0000, v158
	v_lshlrev_b32_e32 v158, 16, v159
	v_and_b32_e32 v159, 0xffff0000, v159
	v_pk_add_f32 v[64:65], v[64:65], v[142:143]
	v_pk_add_f32 v[62:63], v[62:63], v[146:147]
	v_pk_add_f32 v[60:61], v[60:61], v[144:145]
	v_pk_add_f32 v[58:59], v[58:59], v[160:161]
	v_pk_add_f32 v[56:57], v[56:57], v[156:157]
	v_pk_add_f32 v[54:55], v[54:55], v[162:163]
	v_pk_add_f32 v[52:53], v[52:53], v[158:159]
	v_pk_add_f32 v[50:51], v[50:51], v[164:165]
	v_mul_f32_e32 v142, v63, v63
	v_mul_f32_e32 v143, v65, v65
	v_mul_f32_e32 v144, v59, v59
	v_mul_f32_e32 v145, v61, v61
	v_mul_f32_e32 v146, v55, v55
	v_mul_f32_e32 v147, v57, v57
	v_mul_f32_e32 v153, v51, v51
	v_mul_f32_e32 v155, v53, v53
	v_fmac_f32_e32 v142, v62, v62
	v_fmac_f32_e32 v143, v64, v64
	v_fmac_f32_e32 v144, v58, v58
	v_fmac_f32_e32 v145, v60, v60
	v_fmac_f32_e32 v146, v54, v54
	v_fmac_f32_e32 v147, v56, v56
	v_fmac_f32_e32 v153, v50, v50
	v_fmac_f32_e32 v155, v52, v52
	v_add_f32_e32 v142, v142, v143
	v_add_f32_e32 v143, v144, v145
	v_add_f32_e32 v144, v146, v147
	v_add_f32_e32 v145, v153, v155
	v_add_f32_e32 v142, v142, v143
	v_add_f32_e32 v143, v144, v145
	v_add_f32_e32 v142, v142, v143
	ds_bpermute_b32 v143, v152, v142
	s_waitcnt lgkmcnt(0)
	v_add_f32_e32 v142, v142, v143
	ds_bpermute_b32 v143, v154, v142
	s_and_saveexec_b64 s[4:5], vcc
	s_cbranch_execz .LBB0_1418
	s_waitcnt lgkmcnt(0)
	v_add_f32_e32 v144, v142, v143
	v_lshlrev_b64 v[142:143], 6, v[78:79]
	v_lshl_add_u64 v[142:143], s[10:11], 0, v[142:143]
	v_lshl_add_u64 v[142:143], s[0:1], 2, v[142:143]
	s_lshl_b32 s6, s50, 2
	s_mov_b32 s7, 0
	v_lshl_add_u64 v[142:143], v[142:143], 0, s[6:7]
	global_store_dword v[142:143], v144, off sc1
; __device__ __forceinline__ float bflo(unsigned u) { return __uint_as_float(u << 16); }
; __device__ __forceinline__ float bfhi(unsigned u) { return __uint_as_float(u & 0xffff0000u); }
; __device__ __forceinline__ float dot4(f32x4 v) { return (v[0] * v[0] + v[1] * v[1]) + (v[2] * v[2] + v[3] * v[3]); }
; __device__ __forceinline__ float quad_sum(float s) { s += __shfl_xor(s, 16); s += __shfl_xor(s, 32); return s; }
; __device__ __forceinline__ void epi_final(f32x4 (&acc)[2][2][4][2], const Unit& u, int wr, int wc, int fr, int fq, const EpiArgs& E, LAS float* rt) {
;     ...
;             const int row = rowb + ai * HALF + m * 16; float ss = 0.f;
; #pragma unroll
;             for (int bj = 0; bj < 2; ++bj) { const int col = u.pn * BM + bj * HALF + wc * 32 + fq * 8;
;                 const u32x4 rb = *(const u32x4*)(E.res + (size_t)row * 1024 + col);
;                 acc[ai][bj][m][0] += (f32x4){bflo(rb.x), bfhi(rb.x), bflo(rb.y), bfhi(rb.y)};
;                 acc[ai][bj][m][1] += (f32x4){bflo(rb.z), bfhi(rb.z), bflo(rb.w), bfhi(rb.w)};
;                 ss += dot4(acc[ai][bj][m][0]) + dot4(acc[ai][bj][m][1]); }
;             ss = quad_sum(ss);
;             if (fq == 0) __hip_atomic_store((unsigned*)E.stOut + (size_t)row * 16 + u.pn * 4 + wc, __float_as_uint(ss), __ATOMIC_RELAXED, __HIP_MEMORY_SCOPE_AGENT);
.LBB0_1418:
	s_or_b64 exec, exec, s[4:5]
	v_add_u32_e32 v142, 0x90, v130
	s_waitcnt lgkmcnt(0)
	v_ashrrev_i32_e32 v143, 31, v142
	v_lshlrev_b64 v[144:145], 11, v[142:143]
	v_lshl_add_u64 v[144:145], s[62:63], 0, v[144:145]
	v_lshl_add_u64 v[156:157], v[132:133], 1, v[144:145]
	s_waitcnt vmcnt(9)
	v_mov_b32_e32 v144, v204
	v_mov_b32_e32 v145, v205
	v_mov_b32_e32 v146, v206
	v_mov_b32_e32 v147, v207
	v_lshlrev_b32_e32 v160, 16, v144
	v_and_b32_e32 v161, 0xffff0000, v144
	v_lshlrev_b32_e32 v144, 16, v145
	v_and_b32_e32 v145, 0xffff0000, v145
	v_lshlrev_b32_e32 v162, 16, v146
	v_and_b32_e32 v163, 0xffff0000, v146
	v_lshlrev_b32_e32 v146, 16, v147
	v_and_b32_e32 v147, 0xffff0000, v147
	v_mov_b32_e32 v156, v208
	v_mov_b32_e32 v157, v209
	v_mov_b32_e32 v158, v210
	v_mov_b32_e32 v159, v211
	v_lshlrev_b32_e32 v164, 16, v156
	v_and_b32_e32 v165, 0xffff0000, v156
	v_lshlrev_b32_e32 v156, 16, v157
	v_and_b32_e32 v157, 0xffff0000, v157
	v_lshlrev_b32_e32 v166, 16, v158
	v_and_b32_e32 v167, 0xffff0000, v158
	v_lshlrev_b32_e32 v158, 16, v159
	v_and_b32_e32 v159, 0xffff0000, v159
	v_pk_add_f32 v[48:49], v[48:49], v[144:145]
	v_pk_add_f32 v[144:145], v[46:47], v[160:161]
	v_pk_add_f32 v[44:45], v[44:45], v[146:147]
	v_pk_add_f32 v[42:43], v[42:43], v[162:163]
	v_pk_add_f32 v[40:41], v[40:41], v[156:157]
	v_pk_add_f32 v[38:39], v[38:39], v[164:165]
	v_pk_add_f32 v[36:37], v[36:37], v[158:159]
	v_pk_add_f32 v[34:35], v[34:35], v[166:167]
	v_mul_f32_e32 v46, v145, v145
	v_mul_f32_e32 v47, v49, v49
	v_mul_f32_e32 v146, v43, v43
	v_mul_f32_e32 v147, v45, v45
	v_mul_f32_e32 v153, v39, v39
	v_mul_f32_e32 v155, v41, v41
	v_mul_f32_e32 v156, v35, v35
	v_mul_f32_e32 v157, v37, v37
	v_fmac_f32_e32 v46, v144, v144
	v_fmac_f32_e32 v47, v48, v48
	v_fmac_f32_e32 v146, v42, v42
	v_fmac_f32_e32 v147, v44, v44
	v_fmac_f32_e32 v153, v38, v38
	v_fmac_f32_e32 v155, v40, v40
	v_fmac_f32_e32 v156, v34, v34
	v_fmac_f32_e32 v157, v36, v36
	v_add_f32_e32 v46, v46, v47
	v_add_f32_e32 v47, v146, v147
	v_add_f32_e32 v146, v153, v155
	v_add_f32_e32 v147, v156, v157
	v_add_f32_e32 v46, v46, v47
	v_add_f32_e32 v47, v146, v147
	v_add_f32_e32 v46, v46, v47
	ds_bpermute_b32 v47, v152, v46
	s_waitcnt lgkmcnt(0)
	v_add_f32_e32 v46, v46, v47
	ds_bpermute_b32 v47, v154, v46
	s_and_saveexec_b64 s[4:5], vcc
	s_cbranch_execz .LBB0_1420
	s_waitcnt lgkmcnt(0)
	v_add_f32_e32 v146, v46, v47
	v_lshlrev_b64 v[46:47], 6, v[142:143]
	v_lshl_add_u64 v[46:47], s[10:11], 0, v[46:47]
	v_lshl_add_u64 v[46:47], s[0:1], 2, v[46:47]
	s_lshl_b32 s6, s50, 2
	s_mov_b32 s7, 0
	v_lshl_add_u64 v[46:47], v[46:47], 0, s[6:7]
	global_store_dword v[46:47], v146, off sc1
.LBB0_1420:
	s_or_b64 exec, exec, s[4:5]
	v_add_u32_e32 v46, 0xa0, v130
	s_waitcnt lgkmcnt(0)
	v_ashrrev_i32_e32 v47, 31, v46
	v_lshlrev_b64 v[146:147], 11, v[46:47]
	v_lshl_add_u64 v[146:147], s[62:63], 0, v[146:147]
	v_lshl_add_u64 v[146:147], v[132:133], 1, v[146:147]
	s_waitcnt vmcnt(8)
	v_mov_b32_e32 v156, v212
	v_mov_b32_e32 v157, v213
	v_mov_b32_e32 v158, v214
	v_mov_b32_e32 v159, v215
	v_lshlrev_b32_e32 v146, 16, v156
	v_and_b32_e32 v147, 0xffff0000, v156
	v_lshlrev_b32_e32 v156, 16, v157
	v_and_b32_e32 v157, 0xffff0000, v157
	v_lshlrev_b32_e32 v164, 16, v158
	v_and_b32_e32 v165, 0xffff0000, v158
	v_lshlrev_b32_e32 v158, 16, v159
	v_and_b32_e32 v159, 0xffff0000, v159
	v_mov_b32_e32 v160, v216
	v_mov_b32_e32 v161, v217
	v_mov_b32_e32 v162, v218
	v_mov_b32_e32 v163, v219
	v_lshlrev_b32_e32 v166, 16, v160
	v_and_b32_e32 v167, 0xffff0000, v160
	v_lshlrev_b32_e32 v160, 16, v161
	v_and_b32_e32 v161, 0xffff0000, v161
	v_lshlrev_b32_e32 v168, 16, v162
	v_and_b32_e32 v169, 0xffff0000, v162
	v_lshlrev_b32_e32 v162, 16, v163
	v_and_b32_e32 v163, 0xffff0000, v163
	v_pk_add_f32 v[32:33], v[32:33], v[156:157]
	v_pk_add_f32 v[30:31], v[30:31], v[146:147]
	v_pk_add_f32 v[28:29], v[28:29], v[158:159]
	v_pk_add_f32 v[26:27], v[26:27], v[164:165]
	v_pk_add_f32 v[24:25], v[24:25], v[160:161]
	v_pk_add_f32 v[22:23], v[22:23], v[166:167]
	v_pk_add_f32 v[20:21], v[20:21], v[162:163]
	v_pk_add_f32 v[18:19], v[18:19], v[168:169]
	v_mul_f32_e32 v146, v31, v31
	v_mul_f32_e32 v147, v33, v33
	v_mul_f32_e32 v153, v27, v27
	v_mul_f32_e32 v155, v29, v29
	v_mul_f32_e32 v156, v23, v23
	v_mul_f32_e32 v157, v25, v25
	v_mul_f32_e32 v158, v19, v19
	v_mul_f32_e32 v159, v21, v21
	v_fmac_f32_e32 v146, v30, v30
	v_fmac_f32_e32 v147, v32, v32
	v_fmac_f32_e32 v153, v26, v26
	v_fmac_f32_e32 v155, v28, v28
	v_fmac_f32_e32 v156, v22, v22
	v_fmac_f32_e32 v157, v24, v24
	v_fmac_f32_e32 v158, v18, v18
	v_fmac_f32_e32 v159, v20, v20
	v_add_f32_e32 v146, v146, v147
	v_add_f32_e32 v147, v153, v155
	v_add_f32_e32 v153, v156, v157
	v_add_f32_e32 v155, v158, v159
	v_add_f32_e32 v146, v146, v147
	v_add_f32_e32 v147, v153, v155
	v_add_f32_e32 v146, v146, v147
	ds_bpermute_b32 v147, v152, v146
	s_waitcnt lgkmcnt(0)
	v_add_f32_e32 v146, v146, v147
	ds_bpermute_b32 v147, v154, v146
	s_and_saveexec_b64 s[4:5], vcc
	s_cbranch_execz .LBB0_1422
	s_waitcnt lgkmcnt(0)
	v_add_f32_e32 v153, v146, v147
	v_lshlrev_b64 v[146:147], 6, v[46:47]
	v_lshl_add_u64 v[146:147], s[10:11], 0, v[146:147]
	v_lshl_add_u64 v[146:147], s[0:1], 2, v[146:147]
	s_lshl_b32 s6, s50, 2
	s_mov_b32 s7, 0
	v_lshl_add_u64 v[146:147], v[146:147], 0, s[6:7]
	global_store_dword v[146:147], v153, off sc1
; __device__ __forceinline__ float bflo(unsigned u) { return __uint_as_float(u << 16); }
; __device__ __forceinline__ float bfhi(unsigned u) { return __uint_as_float(u & 0xffff0000u); }
; __device__ __forceinline__ float dot4(f32x4 v) { return (v[0] * v[0] + v[1] * v[1]) + (v[2] * v[2] + v[3] * v[3]); }
; __device__ __forceinline__ float quad_sum(float s) { s += __shfl_xor(s, 16); s += __shfl_xor(s, 32); return s; }
; __device__ __forceinline__ void epi_final(f32x4 (&acc)[2][2][4][2], const Unit& u, int wr, int wc, int fr, int fq, const EpiArgs& E, LAS float* rt) {
;     ...
;             const int row = rowb + ai * HALF + m * 16; float ss = 0.f;
; #pragma unroll
;             for (int bj = 0; bj < 2; ++bj) { const int col = u.pn * BM + bj * HALF + wc * 32 + fq * 8;
;                 const u32x4 rb = *(const u32x4*)(E.res + (size_t)row * 1024 + col);
;                 acc[ai][bj][m][0] += (f32x4){bflo(rb.x), bfhi(rb.x), bflo(rb.y), bfhi(rb.y)};
;                 acc[ai][bj][m][1] += (f32x4){bflo(rb.z), bfhi(rb.z), bflo(rb.w), bfhi(rb.w)};
;                 ss += dot4(acc[ai][bj][m][0]) + dot4(acc[ai][bj][m][1]); }
;             ss = quad_sum(ss);
;             if (fq == 0) __hip_atomic_store((unsigned*)E.stOut + (size_t)row * 16 + u.pn * 4 + wc, __float_as_uint(ss), __ATOMIC_RELAXED, __HIP_MEMORY_SCOPE_AGENT);
.LBB0_1422:
	s_or_b64 exec, exec, s[4:5]
	v_add_u32_e32 v146, 0xb0, v130
	s_waitcnt lgkmcnt(0)
	v_ashrrev_i32_e32 v147, 31, v146
	v_lshlrev_b64 v[156:157], 11, v[146:147]
	v_lshl_add_u64 v[156:157], s[62:63], 0, v[156:157]
	v_lshl_add_u64 v[160:161], v[132:133], 1, v[156:157]
	s_waitcnt vmcnt(7)
	v_mov_b32_e32 v156, v220
	v_mov_b32_e32 v157, v221
	v_mov_b32_e32 v158, v222
	v_mov_b32_e32 v159, v223
	v_lshlrev_b32_e32 v164, 16, v156
	v_and_b32_e32 v165, 0xffff0000, v156
	v_lshlrev_b32_e32 v156, 16, v157
	v_and_b32_e32 v157, 0xffff0000, v157
	v_lshlrev_b32_e32 v166, 16, v158
	v_and_b32_e32 v167, 0xffff0000, v158
	v_lshlrev_b32_e32 v158, 16, v159
	v_and_b32_e32 v159, 0xffff0000, v159
	v_mov_b32_e32 v160, v224
	v_mov_b32_e32 v161, v225
	v_mov_b32_e32 v162, v226
	v_mov_b32_e32 v163, v227
	v_lshlrev_b32_e32 v168, 16, v160
	v_and_b32_e32 v169, 0xffff0000, v160
	v_lshlrev_b32_e32 v160, 16, v161
	v_and_b32_e32 v161, 0xffff0000, v161
	v_lshlrev_b32_e32 v170, 16, v162
	v_and_b32_e32 v171, 0xffff0000, v162
	v_lshlrev_b32_e32 v162, 16, v163
	v_and_b32_e32 v163, 0xffff0000, v163
	v_pk_add_f32 v[16:17], v[16:17], v[156:157]
	v_pk_add_f32 v[14:15], v[14:15], v[164:165]
	v_pk_add_f32 v[12:13], v[12:13], v[158:159]
	v_pk_add_f32 v[10:11], v[10:11], v[166:167]
	v_pk_add_f32 v[8:9], v[8:9], v[160:161]
	v_pk_add_f32 v[6:7], v[6:7], v[168:169]
	v_pk_add_f32 v[4:5], v[4:5], v[162:163]
	v_pk_add_f32 v[2:3], v[2:3], v[170:171]
	v_mul_f32_e32 v153, v15, v15
	v_mul_f32_e32 v155, v17, v17
	v_mul_f32_e32 v156, v11, v11
	v_mul_f32_e32 v157, v13, v13
	v_mul_f32_e32 v158, v7, v7
	v_mul_f32_e32 v159, v9, v9
	v_mul_f32_e32 v160, v3, v3
	v_mul_f32_e32 v161, v5, v5
	v_fmac_f32_e32 v153, v14, v14
	v_fmac_f32_e32 v155, v16, v16
	v_fmac_f32_e32 v156, v10, v10
	v_fmac_f32_e32 v157, v12, v12
	v_fmac_f32_e32 v158, v6, v6
	v_fmac_f32_e32 v159, v8, v8
	v_fmac_f32_e32 v160, v2, v2
	v_fmac_f32_e32 v161, v4, v4
	v_add_f32_e32 v153, v153, v155
	v_add_f32_e32 v155, v156, v157
	v_add_f32_e32 v156, v158, v159
	v_add_f32_e32 v157, v160, v161
	v_add_f32_e32 v153, v153, v155
	v_add_f32_e32 v155, v156, v157
	v_add_f32_e32 v153, v153, v155
	ds_bpermute_b32 v152, v152, v153
	s_waitcnt lgkmcnt(0)
	v_add_f32_e32 v152, v153, v152
	ds_bpermute_b32 v153, v154, v152
	s_and_saveexec_b64 s[4:5], vcc
	s_cbranch_execz .LBB0_1424
	s_waitcnt lgkmcnt(0)
	v_add_f32_e32 v154, v152, v153
	v_lshlrev_b64 v[152:153], 6, v[146:147]
	v_lshl_add_u64 v[152:153], s[10:11], 0, v[152:153]
	v_lshl_add_u64 v[152:153], s[0:1], 2, v[152:153]
	s_lshl_b32 s0, s50, 2
	s_mov_b32 s1, 0
	v_lshl_add_u64 v[152:153], v[152:153], 0, s[0:1]
	global_store_dword v[152:153], v154, off sc1
